# adds: row-sum shuffles of the three row-statistics exchanges use v_permlane16/32_swap instead of ds_bpermute round trips
# speedup vs baseline: 1.0020x; 1.0004x over previous
.LBB0_574:
	s_lshl_b32 s0, s15, 5
	s_lshl_b32 s6, s16, 8
	s_or_b32 s0, s6, s0
	s_lshl_b32 s40, s14, 8
	v_and_or_b32 v210, v150, 24, s0
	s_add_i32 s0, s40, s61
	v_or_b32_e32 v130, s0, v219
	v_ashrrev_i32_e32 v211, 31, v210
	v_ashrrev_i32_e32 v131, 31, v130
	v_lshl_add_u64 v[132:133], v[210:211], 1, s[38:39]
	v_lshlrev_b64 v[134:135], 11, v[130:131]
	v_lshl_add_u64 v[134:135], v[132:133], 0, v[134:135]
	s_barrier
	v_lshlrev_b32_e32 v234, 4, v1
	v_add_u32_e32 v234, s49, v234
	v_add_u32_e32 v235, 0x10000, v234
	ds_read_b128 v[194:197], v235 offset:0
	ds_read_b128 v[186:189], v235 offset:8192
	v_or_b32_e32 v134, 16, v130
	v_ashrrev_i32_e32 v135, 31, v134
	v_lshlrev_b64 v[134:135], 11, v[134:135]
	v_lshl_add_u64 v[134:135], v[132:133], 0, v[134:135]
	ds_read_b128 v[182:185], v235 offset:16384
	ds_read_b128 v[178:181], v235 offset:24576
	v_or_b32_e32 v134, 32, v130
	v_ashrrev_i32_e32 v135, 31, v134
	v_lshlrev_b64 v[134:135], 11, v[134:135]
	v_lshl_add_u64 v[134:135], v[132:133], 0, v[134:135]
	ds_read_b128 v[174:177], v234 offset:0
	ds_read_b128 v[170:173], v234 offset:8192
	v_or_b32_e32 v134, 48, v130
	v_ashrrev_i32_e32 v135, 31, v134
	v_lshlrev_b64 v[134:135], 11, v[134:135]
	v_lshl_add_u64 v[134:135], v[132:133], 0, v[134:135]
	ds_read_b128 v[166:169], v234 offset:16384
	ds_read_b128 v[162:165], v234 offset:24576
	v_add_u32_e32 v134, 0x80, v130
	v_ashrrev_i32_e32 v135, 31, v134
	v_lshlrev_b64 v[134:135], 11, v[134:135]
	v_lshl_add_u64 v[134:135], v[132:133], 0, v[134:135]
	ds_read_b128 v[158:161], v235 offset:32768
	ds_read_b128 v[154:157], v235 offset:40960
	v_add_u32_e32 v134, 0x90, v130
	v_ashrrev_i32_e32 v135, 31, v134
	v_lshlrev_b64 v[134:135], 11, v[134:135]
	v_lshl_add_u64 v[134:135], v[132:133], 0, v[134:135]
	ds_read_b128 v[150:153], v235 offset:49152
	ds_read_b128 v[146:149], v235 offset:57344
	v_add_u32_e32 v134, 0xa0, v130
	v_add_u32_e32 v130, 0xb0, v130
	v_ashrrev_i32_e32 v135, 31, v134
	v_ashrrev_i32_e32 v131, 31, v130
	v_lshlrev_b64 v[134:135], 11, v[134:135]
	v_lshlrev_b64 v[130:131], 11, v[130:131]
	v_lshl_add_u64 v[134:135], v[132:133], 0, v[134:135]
	v_lshl_add_u64 v[130:131], v[132:133], 0, v[130:131]
	ds_read_b128 v[142:145], v234 offset:32768
	ds_read_b128 v[138:141], v234 offset:40960
	s_nop 0
	global_load_dwordx4 v[134:137], v[130:131], off
	s_nop 0
	global_load_dwordx4 v[130:133], v[130:131], off offset:256
	s_waitcnt lgkmcnt(0)
	s_barrier
	v_mbcnt_lo_u32_b32 v190, -1, 0
	v_mbcnt_hi_u32_b32 v190, -1, v190
	v_and_b32_e32 v192, 64, v190
	v_xor_b32_e32 v191, 16, v190
	v_add_u32_e32 v192, 64, v192
	v_cmp_lt_i32_e32 vcc, v191, v192
	v_mul_f32_e32 v193, v129, v129
	v_fmac_f32_e32 v193, v128, v128
	v_cndmask_b32_e32 v191, v190, v191, vcc
	v_lshlrev_b32_e32 v220, 2, v191
	v_mul_f32_e32 v191, v127, v127
	v_fmac_f32_e32 v191, v126, v126
	v_add_f32_e32 v191, v191, v193
	v_mul_f32_e32 v193, v123, v123
	v_mul_f32_e32 v198, v125, v125
	v_fmac_f32_e32 v193, v122, v122
	v_fmac_f32_e32 v198, v124, v124
	v_add_f32_e32 v193, v193, v198
	v_add_f32_e32 v191, v193, v191
	v_mul_f32_e32 v193, v119, v119
	v_mul_f32_e32 v198, v121, v121
	v_fmac_f32_e32 v193, v118, v118
	v_fmac_f32_e32 v198, v120, v120
	v_add_f32_e32 v193, v193, v198
	v_add_f32_e32 v191, v193, v191
	v_mul_f32_e32 v193, v115, v115
	v_mul_f32_e32 v198, v117, v117
	v_fmac_f32_e32 v193, v114, v114
	v_fmac_f32_e32 v198, v116, v116
	v_add_f32_e32 v193, v193, v198
	v_add_f32_e32 v191, v193, v191
	v_mov_b32_e32 v193, v191
	s_nop 1
	v_permlane16_swap_b32_e32 v191, v193
	v_xor_b32_e32 v198, 32, v190
	v_cmp_lt_i32_e32 vcc, v198, v192
	s_lshl_b32 s0, s15, 2
	v_cmp_gt_u32_e64 s[6:7], 16, v1
	v_cndmask_b32_e32 v190, v190, v198, vcc
	v_lshlrev_b32_e32 v221, 2, v190
	s_waitcnt lgkmcnt(0)
	v_add_f32_e32 v190, v191, v193
	v_mov_b32_e32 v191, v190
	s_nop 1
	v_permlane32_swap_b32_e32 v190, v191
	s_add_i32 s15, s0, 0
	s_and_saveexec_b64 s[8:9], s[6:7]
	s_cbranch_execz .LBB0_576
	s_lshl_b32 s0, s1, 10
	s_add_i32 s0, s15, s0
	v_lshl_add_u32 v192, v219, 4, s0
	s_waitcnt lgkmcnt(0)
	v_add_f32_e32 v190, v190, v191
	ds_write_b32 v192, v190
.LBB0_576:
	s_or_b64 exec, exec, s[8:9]
	v_mul_f32_e32 v190, v111, v111
	s_waitcnt lgkmcnt(0)
	v_mul_f32_e32 v191, v113, v113
	v_fmac_f32_e32 v190, v110, v110
	v_fmac_f32_e32 v191, v112, v112
	v_add_f32_e32 v190, v190, v191
	v_mul_f32_e32 v191, v107, v107
	v_mul_f32_e32 v192, v109, v109
	v_fmac_f32_e32 v191, v106, v106
	v_fmac_f32_e32 v192, v108, v108
	v_add_f32_e32 v191, v191, v192
	v_add_f32_e32 v190, v191, v190
	v_mul_f32_e32 v191, v103, v103
	v_mul_f32_e32 v192, v105, v105
	v_fmac_f32_e32 v191, v102, v102
	v_fmac_f32_e32 v192, v104, v104
	v_add_f32_e32 v191, v191, v192
	v_add_f32_e32 v190, v191, v190
	v_mul_f32_e32 v191, v99, v99
	v_mul_f32_e32 v192, v101, v101
	v_fmac_f32_e32 v191, v98, v98
	v_fmac_f32_e32 v192, v100, v100
	v_add_f32_e32 v191, v191, v192
	v_add_f32_e32 v190, v191, v190
	v_mov_b32_e32 v191, v190
	s_nop 1
	v_permlane16_swap_b32_e32 v190, v191
	s_waitcnt lgkmcnt(0)
	v_add_f32_e32 v190, v190, v191
	v_mov_b32_e32 v191, v190
	s_nop 1
	v_permlane32_swap_b32_e32 v190, v191
	s_and_saveexec_b64 s[8:9], s[6:7]
	s_cbranch_execz .LBB0_578
	s_lshl_b32 s0, s1, 10
	s_add_i32 s0, s15, s0
	v_lshl_add_u32 v192, v219, 4, s0
	s_waitcnt lgkmcnt(0)
	v_add_f32_e32 v190, v190, v191
	ds_write_b32 v192, v190 offset:256
.LBB0_578:
	s_or_b64 exec, exec, s[8:9]
	v_mul_f32_e32 v190, v95, v95
	s_waitcnt lgkmcnt(0)
	v_mul_f32_e32 v191, v97, v97
	v_fmac_f32_e32 v190, v94, v94
	v_fmac_f32_e32 v191, v96, v96
	v_add_f32_e32 v190, v190, v191
	v_mul_f32_e32 v191, v91, v91
	v_mul_f32_e32 v192, v93, v93
	v_fmac_f32_e32 v191, v90, v90
	v_fmac_f32_e32 v192, v92, v92
	v_add_f32_e32 v191, v191, v192
	v_add_f32_e32 v190, v191, v190
	v_mul_f32_e32 v191, v87, v87
	v_mul_f32_e32 v192, v89, v89
	v_fmac_f32_e32 v191, v86, v86
	v_fmac_f32_e32 v192, v88, v88
	v_add_f32_e32 v191, v191, v192
	v_add_f32_e32 v190, v191, v190
	v_mul_f32_e32 v191, v83, v83
	v_mul_f32_e32 v192, v85, v85
	v_fmac_f32_e32 v191, v82, v82
	v_fmac_f32_e32 v192, v84, v84
	v_add_f32_e32 v191, v191, v192
	v_add_f32_e32 v190, v191, v190
	v_mov_b32_e32 v191, v190
	s_nop 1
	v_permlane16_swap_b32_e32 v190, v191
	s_waitcnt lgkmcnt(0)
	v_add_f32_e32 v190, v190, v191
	v_mov_b32_e32 v191, v190
	s_nop 1
	v_permlane32_swap_b32_e32 v190, v191
	s_and_saveexec_b64 s[8:9], s[6:7]
	s_cbranch_execz .LBB0_580
	s_lshl_b32 s0, s1, 10
	s_add_i32 s0, s15, s0
	v_lshl_add_u32 v192, v219, 4, s0
	s_waitcnt lgkmcnt(0)
	v_add_f32_e32 v190, v190, v191
	ds_write_b32 v192, v190 offset:512
.LBB0_580:
	s_or_b64 exec, exec, s[8:9]
	v_mul_f32_e32 v190, v79, v79
	s_waitcnt lgkmcnt(0)
	v_mul_f32_e32 v191, v81, v81
	v_fmac_f32_e32 v190, v78, v78
	v_fmac_f32_e32 v191, v80, v80
	v_add_f32_e32 v190, v190, v191
	v_mul_f32_e32 v191, v75, v75
	v_mul_f32_e32 v192, v77, v77
	v_fmac_f32_e32 v191, v74, v74
	v_fmac_f32_e32 v192, v76, v76
	v_add_f32_e32 v191, v191, v192
	v_add_f32_e32 v190, v191, v190
	v_mul_f32_e32 v191, v71, v71
	v_mul_f32_e32 v192, v73, v73
	v_fmac_f32_e32 v191, v70, v70
	v_fmac_f32_e32 v192, v72, v72
	v_add_f32_e32 v191, v191, v192
	v_add_f32_e32 v190, v191, v190
	v_mul_f32_e32 v191, v67, v67
	v_mul_f32_e32 v192, v69, v69
	v_fmac_f32_e32 v191, v66, v66
	v_fmac_f32_e32 v192, v68, v68
	v_add_f32_e32 v191, v191, v192
	v_add_f32_e32 v190, v191, v190
	v_mov_b32_e32 v191, v190
	s_nop 1
	v_permlane16_swap_b32_e32 v190, v191
	s_waitcnt lgkmcnt(0)
	v_add_f32_e32 v190, v190, v191
	v_mov_b32_e32 v191, v190
	s_nop 1
	v_permlane32_swap_b32_e32 v190, v191
	s_and_saveexec_b64 s[8:9], s[6:7]
	s_cbranch_execz .LBB0_582
	s_lshl_b32 s0, s1, 10
	s_add_i32 s0, s15, s0
	v_lshl_add_u32 v192, v219, 4, s0
	s_waitcnt lgkmcnt(0)
	v_add_f32_e32 v190, v190, v191
	ds_write_b32 v192, v190 offset:768
.LBB0_582:
	s_or_b64 exec, exec, s[8:9]
	v_mul_f32_e32 v190, v63, v63
	s_waitcnt lgkmcnt(0)
	v_mul_f32_e32 v191, v65, v65
	v_fmac_f32_e32 v190, v62, v62
	v_fmac_f32_e32 v191, v64, v64
	v_add_f32_e32 v190, v190, v191
	v_mul_f32_e32 v191, v59, v59
	v_mul_f32_e32 v192, v61, v61
	v_fmac_f32_e32 v191, v58, v58
	v_fmac_f32_e32 v192, v60, v60
	v_add_f32_e32 v191, v191, v192
	v_add_f32_e32 v190, v191, v190
	v_mul_f32_e32 v191, v55, v55
	v_mul_f32_e32 v192, v57, v57
	v_fmac_f32_e32 v191, v54, v54
	v_fmac_f32_e32 v192, v56, v56
	v_add_f32_e32 v191, v191, v192
	v_add_f32_e32 v190, v191, v190
	v_mul_f32_e32 v191, v51, v51
	v_mul_f32_e32 v192, v53, v53
	v_fmac_f32_e32 v191, v50, v50
	v_fmac_f32_e32 v192, v52, v52
	v_add_f32_e32 v191, v191, v192
	v_add_f32_e32 v190, v191, v190
	v_mov_b32_e32 v191, v190
	s_nop 1
	v_permlane16_swap_b32_e32 v190, v191
	s_waitcnt lgkmcnt(0)
	v_add_f32_e32 v190, v190, v191
	v_mov_b32_e32 v191, v190
	s_nop 1
	v_permlane32_swap_b32_e32 v190, v191
	s_and_saveexec_b64 s[8:9], s[6:7]
	s_cbranch_execz .LBB0_584
	s_lshl_b32 s0, s1, 10
	s_add_i32 s0, s15, s0
	v_lshl_add_u32 v192, v219, 4, s0
	s_waitcnt lgkmcnt(0)
	v_add_f32_e32 v190, v190, v191
	ds_write_b32 v192, v190 offset:2048
.LBB0_584:
	s_or_b64 exec, exec, s[8:9]
	v_mul_f32_e32 v190, v47, v47
	s_waitcnt lgkmcnt(0)
	v_mul_f32_e32 v191, v49, v49
	v_fmac_f32_e32 v190, v46, v46
	v_fmac_f32_e32 v191, v48, v48
	v_add_f32_e32 v190, v190, v191
	v_mul_f32_e32 v191, v43, v43
	v_mul_f32_e32 v192, v45, v45
	v_fmac_f32_e32 v191, v42, v42
	v_fmac_f32_e32 v192, v44, v44
	v_add_f32_e32 v191, v191, v192
	v_add_f32_e32 v190, v191, v190
	v_mul_f32_e32 v191, v39, v39
	v_mul_f32_e32 v192, v41, v41
	v_fmac_f32_e32 v191, v38, v38
	v_fmac_f32_e32 v192, v40, v40
	v_add_f32_e32 v191, v191, v192
	v_add_f32_e32 v190, v191, v190
	v_mul_f32_e32 v191, v35, v35
	v_mul_f32_e32 v192, v37, v37
	v_fmac_f32_e32 v191, v34, v34
	v_fmac_f32_e32 v192, v36, v36
	v_add_f32_e32 v191, v191, v192
	v_add_f32_e32 v190, v191, v190
	v_mov_b32_e32 v191, v190
	s_nop 1
	v_permlane16_swap_b32_e32 v190, v191
	s_waitcnt lgkmcnt(0)
	v_add_f32_e32 v190, v190, v191
	v_mov_b32_e32 v191, v190
	s_nop 1
	v_permlane32_swap_b32_e32 v190, v191
	s_and_saveexec_b64 s[8:9], s[6:7]
	s_cbranch_execz .LBB0_586
	s_lshl_b32 s0, s1, 10
	s_add_i32 s0, s15, s0
	v_lshl_add_u32 v192, v219, 4, s0
	s_waitcnt lgkmcnt(0)
	v_add_f32_e32 v190, v190, v191
	ds_write_b32 v192, v190 offset:2304
.LBB0_586:
	s_or_b64 exec, exec, s[8:9]
	v_mul_f32_e32 v190, v31, v31
	s_waitcnt lgkmcnt(0)
	v_mul_f32_e32 v191, v33, v33
	v_fmac_f32_e32 v190, v30, v30
	v_fmac_f32_e32 v191, v32, v32
	v_add_f32_e32 v190, v190, v191
	v_mul_f32_e32 v191, v27, v27
	v_mul_f32_e32 v192, v29, v29
	v_fmac_f32_e32 v191, v26, v26
	v_fmac_f32_e32 v192, v28, v28
	v_add_f32_e32 v191, v191, v192
	v_add_f32_e32 v190, v191, v190
	v_mul_f32_e32 v191, v23, v23
	v_mul_f32_e32 v192, v25, v25
	v_fmac_f32_e32 v191, v22, v22
	v_fmac_f32_e32 v192, v24, v24
	v_add_f32_e32 v191, v191, v192
	v_add_f32_e32 v190, v191, v190
	v_mul_f32_e32 v191, v19, v19
	v_mul_f32_e32 v192, v21, v21
	v_fmac_f32_e32 v191, v18, v18
	v_fmac_f32_e32 v192, v20, v20
	v_add_f32_e32 v191, v191, v192
	v_add_f32_e32 v190, v191, v190
	v_mov_b32_e32 v191, v190
	s_nop 1
	v_permlane16_swap_b32_e32 v190, v191
	s_waitcnt lgkmcnt(0)
	v_add_f32_e32 v190, v190, v191
	v_mov_b32_e32 v191, v190
	s_nop 1
	v_permlane32_swap_b32_e32 v190, v191
	s_and_saveexec_b64 s[8:9], s[6:7]
	s_cbranch_execz .LBB0_588
	s_lshl_b32 s0, s1, 10
	s_add_i32 s0, s15, s0
	v_lshl_add_u32 v192, v219, 4, s0
	s_waitcnt lgkmcnt(0)
	v_add_f32_e32 v190, v190, v191
	ds_write_b32 v192, v190 offset:2560
.LBB0_588:
	s_or_b64 exec, exec, s[8:9]
	v_mul_f32_e32 v190, v15, v15
	s_waitcnt lgkmcnt(0)
	v_mul_f32_e32 v191, v17, v17
	v_fmac_f32_e32 v190, v14, v14
	v_fmac_f32_e32 v191, v16, v16
	v_add_f32_e32 v190, v190, v191
	v_mul_f32_e32 v191, v11, v11
	v_mul_f32_e32 v192, v13, v13
	v_fmac_f32_e32 v191, v10, v10
	v_fmac_f32_e32 v192, v12, v12
	v_add_f32_e32 v191, v191, v192
	v_add_f32_e32 v190, v191, v190
	v_mul_f32_e32 v191, v7, v7
	v_mul_f32_e32 v192, v9, v9
	v_fmac_f32_e32 v191, v6, v6
	v_fmac_f32_e32 v192, v8, v8
	v_add_f32_e32 v191, v191, v192
	v_add_f32_e32 v190, v191, v190
	v_mul_f32_e32 v191, v3, v3
	v_mul_f32_e32 v192, v5, v5
	v_fmac_f32_e32 v191, v2, v2
	v_fmac_f32_e32 v192, v4, v4
	v_add_f32_e32 v191, v191, v192
	v_add_f32_e32 v190, v191, v190
	v_mov_b32_e32 v191, v190
	s_nop 1
	v_permlane16_swap_b32_e32 v190, v191
	s_waitcnt lgkmcnt(0)
	v_add_f32_e32 v190, v190, v191
	v_mov_b32_e32 v191, v190
	s_nop 1
	v_permlane32_swap_b32_e32 v190, v191
	s_and_saveexec_b64 s[8:9], s[6:7]
	s_cbranch_execz .LBB0_590
	s_lshl_b32 s0, s1, 10
	s_add_i32 s0, s15, s0
	v_lshl_add_u32 v192, v219, 4, s0
	s_waitcnt lgkmcnt(0)
	v_add_f32_e32 v190, v190, v191
	ds_write_b32 v192, v190 offset:2816

.LBB0_629:
	v_lshlrev_b32_e32 v138, 16, v134
	v_and_b32_e32 v139, 0xffff0000, v134
	v_lshlrev_b32_e32 v134, 16, v135
	v_and_b32_e32 v135, 0xffff0000, v135
	s_waitcnt lgkmcnt(0)
	v_pk_mul_f32 v[16:17], v[16:17], v[146:147] op_sel_hi:[1,0]
	v_pk_mul_f32 v[8:9], v[8:9], v[146:147] op_sel_hi:[1,0]
	v_pk_fma_f32 v[16:17], v[208:209], v[16:17], v[134:135]
	v_lshlrev_b32_e32 v134, 16, v130
	v_and_b32_e32 v135, 0xffff0000, v130
	v_lshlrev_b32_e32 v130, 16, v131
	v_and_b32_e32 v131, 0xffff0000, v131
	v_pk_fma_f32 v[8:9], v[200:201], v[8:9], v[130:131]
	v_mul_f32_e32 v130, v127, v127
	v_mul_f32_e32 v131, v129, v129
	v_pk_mul_f32 v[6:7], v[6:7], v[146:147] op_sel_hi:[1,0]
	v_fmac_f32_e32 v130, v126, v126
	v_fmac_f32_e32 v131, v128, v128
	v_pk_fma_f32 v[6:7], v[198:199], v[6:7], v[134:135]
	v_add_f32_e32 v130, v130, v131
	v_mul_f32_e32 v131, v123, v123
	v_mul_f32_e32 v134, v125, v125
	v_fmac_f32_e32 v131, v122, v122
	v_fmac_f32_e32 v134, v124, v124
	v_add_f32_e32 v131, v131, v134
	v_add_f32_e32 v130, v130, v131
	v_mul_f32_e32 v131, v119, v119
	v_mul_f32_e32 v134, v121, v121
	v_fmac_f32_e32 v131, v118, v118
	v_fmac_f32_e32 v134, v120, v120
	v_add_f32_e32 v131, v131, v134
	v_add_f32_e32 v130, v131, v130
	v_mul_f32_e32 v131, v115, v115
	v_mul_f32_e32 v134, v117, v117
	v_fmac_f32_e32 v131, v114, v114
	v_fmac_f32_e32 v134, v116, v116
	v_add_f32_e32 v131, v131, v134
	v_add_f32_e32 v130, v131, v130
	v_mov_b32_e32 v131, v130
	s_nop 1
	v_permlane16_swap_b32_e32 v130, v131
	v_lshlrev_b32_e32 v140, 16, v136
	v_and_b32_e32 v141, 0xffff0000, v136
	v_lshlrev_b32_e32 v136, 16, v137
	v_and_b32_e32 v137, 0xffff0000, v137
	v_pk_mul_f32 v[12:13], v[12:13], v[146:147] op_sel_hi:[1,0]
	s_waitcnt lgkmcnt(0)
	v_add_f32_e32 v130, v130, v131
	v_pk_mul_f32 v[14:15], v[14:15], v[146:147] op_sel_hi:[1,0]
	v_pk_mul_f32 v[10:11], v[10:11], v[146:147] op_sel_hi:[1,0]
	v_pk_fma_f32 v[12:13], v[204:205], v[12:13], v[136:137]
	v_lshlrev_b32_e32 v136, 16, v132
	v_and_b32_e32 v137, 0xffff0000, v132
	v_lshlrev_b32_e32 v132, 16, v133
	v_and_b32_e32 v133, 0xffff0000, v133
	v_pk_mul_f32 v[4:5], v[4:5], v[146:147] op_sel_hi:[1,0]
	v_pk_mul_f32 v[2:3], v[2:3], v[146:147] op_sel_hi:[1,0]
	v_mov_b32_e32 v131, v130
	s_nop 1
	v_permlane32_swap_b32_e32 v130, v131
	v_pk_fma_f32 v[14:15], v[206:207], v[14:15], v[138:139]
	v_pk_fma_f32 v[10:11], v[202:203], v[10:11], v[140:141]
	v_pk_fma_f32 v[4:5], v[192:193], v[4:5], v[132:133]
	v_pk_fma_f32 v[2:3], v[190:191], v[2:3], v[136:137]
	s_nop 0
	s_and_saveexec_b64 s[12:13], s[6:7]
	s_xor_b64 s[12:13], exec, s[12:13]
	s_cbranch_execz .LBB0_631
	s_lshl_b32 s0, s1, 10
	s_add_i32 s0, s15, s0
	v_lshl_add_u32 v132, v219, 4, s0
	s_waitcnt lgkmcnt(0)
	v_add_f32_e32 v130, v130, v131
	ds_write_b32 v132, v130
.LBB0_631:
	s_or_b64 exec, exec, s[12:13]
	v_mul_f32_e32 v130, v111, v111
	s_waitcnt lgkmcnt(0)
	v_mul_f32_e32 v131, v113, v113
	v_fmac_f32_e32 v130, v110, v110
	v_fmac_f32_e32 v131, v112, v112
	v_add_f32_e32 v130, v130, v131
	v_mul_f32_e32 v131, v107, v107
	v_mul_f32_e32 v132, v109, v109
	v_fmac_f32_e32 v131, v106, v106
	v_fmac_f32_e32 v132, v108, v108
	v_add_f32_e32 v131, v131, v132
	v_add_f32_e32 v130, v130, v131
	v_mul_f32_e32 v131, v103, v103
	v_mul_f32_e32 v132, v105, v105
	v_fmac_f32_e32 v131, v102, v102
	v_fmac_f32_e32 v132, v104, v104
	v_add_f32_e32 v131, v131, v132
	v_add_f32_e32 v130, v131, v130
	v_mul_f32_e32 v131, v99, v99
	v_mul_f32_e32 v132, v101, v101
	v_fmac_f32_e32 v131, v98, v98
	v_fmac_f32_e32 v132, v100, v100
	v_add_f32_e32 v131, v131, v132
	v_add_f32_e32 v130, v131, v130
	v_mov_b32_e32 v131, v130
	s_nop 1
	v_permlane16_swap_b32_e32 v130, v131
	s_waitcnt lgkmcnt(0)
	v_add_f32_e32 v130, v130, v131
	v_mov_b32_e32 v131, v130
	s_nop 1
	v_permlane32_swap_b32_e32 v130, v131
	s_and_saveexec_b64 s[12:13], s[6:7]
	s_cbranch_execz .LBB0_633
	s_lshl_b32 s0, s1, 10
	s_add_i32 s0, s15, s0
	v_lshl_add_u32 v132, v219, 4, s0
	s_waitcnt lgkmcnt(0)
	v_add_f32_e32 v130, v130, v131
	ds_write_b32 v132, v130 offset:256
.LBB0_633:
	s_or_b64 exec, exec, s[12:13]
	v_mul_f32_e32 v130, v95, v95
	s_waitcnt lgkmcnt(0)
	v_mul_f32_e32 v131, v97, v97
	v_fmac_f32_e32 v130, v94, v94
	v_fmac_f32_e32 v131, v96, v96
	v_add_f32_e32 v130, v130, v131
	v_mul_f32_e32 v131, v91, v91
	v_mul_f32_e32 v132, v93, v93
	v_fmac_f32_e32 v131, v90, v90
	v_fmac_f32_e32 v132, v92, v92
	v_add_f32_e32 v131, v131, v132
	v_add_f32_e32 v130, v130, v131
	v_mul_f32_e32 v131, v87, v87
	v_mul_f32_e32 v132, v89, v89
	v_fmac_f32_e32 v131, v86, v86
	v_fmac_f32_e32 v132, v88, v88
	v_add_f32_e32 v131, v131, v132
	v_add_f32_e32 v130, v131, v130
	v_mul_f32_e32 v131, v83, v83
	v_mul_f32_e32 v132, v85, v85
	v_fmac_f32_e32 v131, v82, v82
	v_fmac_f32_e32 v132, v84, v84
	v_add_f32_e32 v131, v131, v132
	v_add_f32_e32 v130, v131, v130
	v_mov_b32_e32 v131, v130
	s_nop 1
	v_permlane16_swap_b32_e32 v130, v131
	s_waitcnt lgkmcnt(0)
	v_add_f32_e32 v130, v130, v131
	v_mov_b32_e32 v131, v130
	s_nop 1
	v_permlane32_swap_b32_e32 v130, v131
	s_and_saveexec_b64 s[12:13], s[6:7]
	s_cbranch_execz .LBB0_635
	s_lshl_b32 s0, s1, 10
	s_add_i32 s0, s15, s0
	v_lshl_add_u32 v132, v219, 4, s0
	s_waitcnt lgkmcnt(0)
	v_add_f32_e32 v130, v130, v131
	ds_write_b32 v132, v130 offset:512
.LBB0_635:
	s_or_b64 exec, exec, s[12:13]
	v_mul_f32_e32 v130, v79, v79
	s_waitcnt lgkmcnt(0)
	v_mul_f32_e32 v131, v81, v81
	v_fmac_f32_e32 v130, v78, v78
	v_fmac_f32_e32 v131, v80, v80
	v_add_f32_e32 v130, v130, v131
	v_mul_f32_e32 v131, v75, v75
	v_mul_f32_e32 v132, v77, v77
	v_fmac_f32_e32 v131, v74, v74
	v_fmac_f32_e32 v132, v76, v76
	v_add_f32_e32 v131, v131, v132
	v_add_f32_e32 v130, v130, v131
	v_mul_f32_e32 v131, v71, v71
	v_mul_f32_e32 v132, v73, v73
	v_fmac_f32_e32 v131, v70, v70
	v_fmac_f32_e32 v132, v72, v72
	v_add_f32_e32 v131, v131, v132
	v_add_f32_e32 v130, v131, v130
	v_mul_f32_e32 v131, v67, v67
	v_mul_f32_e32 v132, v69, v69
	v_fmac_f32_e32 v131, v66, v66
	v_fmac_f32_e32 v132, v68, v68
	v_add_f32_e32 v131, v131, v132
	v_add_f32_e32 v130, v131, v130
	v_mov_b32_e32 v131, v130
	s_nop 1
	v_permlane16_swap_b32_e32 v130, v131
	s_waitcnt lgkmcnt(0)
	v_add_f32_e32 v130, v130, v131
	v_mov_b32_e32 v131, v130
	s_nop 1
	v_permlane32_swap_b32_e32 v130, v131
	s_and_saveexec_b64 s[12:13], s[6:7]
	s_cbranch_execz .LBB0_637
	s_lshl_b32 s0, s1, 10
	s_add_i32 s0, s15, s0
	v_lshl_add_u32 v132, v219, 4, s0
	s_waitcnt lgkmcnt(0)
	v_add_f32_e32 v130, v130, v131
	ds_write_b32 v132, v130 offset:768
.LBB0_637:
	s_or_b64 exec, exec, s[12:13]
	v_mul_f32_e32 v130, v63, v63
	s_waitcnt lgkmcnt(0)
	v_mul_f32_e32 v131, v65, v65
	v_fmac_f32_e32 v130, v62, v62
	v_fmac_f32_e32 v131, v64, v64
	v_add_f32_e32 v130, v130, v131
	v_mul_f32_e32 v131, v59, v59
	v_mul_f32_e32 v132, v61, v61
	v_fmac_f32_e32 v131, v58, v58
	v_fmac_f32_e32 v132, v60, v60
	v_add_f32_e32 v131, v131, v132
	v_add_f32_e32 v130, v130, v131
	v_mul_f32_e32 v131, v55, v55
	v_mul_f32_e32 v132, v57, v57
	v_fmac_f32_e32 v131, v54, v54
	v_fmac_f32_e32 v132, v56, v56
	v_add_f32_e32 v131, v131, v132
	v_add_f32_e32 v130, v131, v130
	v_mul_f32_e32 v131, v51, v51
	v_mul_f32_e32 v132, v53, v53
	v_fmac_f32_e32 v131, v50, v50
	v_fmac_f32_e32 v132, v52, v52
	v_add_f32_e32 v131, v131, v132
	v_add_f32_e32 v130, v131, v130
	v_mov_b32_e32 v131, v130
	s_nop 1
	v_permlane16_swap_b32_e32 v130, v131
	s_waitcnt lgkmcnt(0)
	v_add_f32_e32 v130, v130, v131
	v_mov_b32_e32 v131, v130
	s_nop 1
	v_permlane32_swap_b32_e32 v130, v131
	s_and_saveexec_b64 s[12:13], s[6:7]
	s_cbranch_execz .LBB0_639
	s_lshl_b32 s0, s1, 10
	s_add_i32 s0, s15, s0
	v_lshl_add_u32 v132, v219, 4, s0
	s_waitcnt lgkmcnt(0)
	v_add_f32_e32 v130, v130, v131
	ds_write_b32 v132, v130 offset:2048
.LBB0_639:
	s_or_b64 exec, exec, s[12:13]
	v_mul_f32_e32 v130, v47, v47
	s_waitcnt lgkmcnt(0)
	v_mul_f32_e32 v131, v49, v49
	v_fmac_f32_e32 v130, v46, v46
	v_fmac_f32_e32 v131, v48, v48
	v_add_f32_e32 v130, v130, v131
	v_mul_f32_e32 v131, v43, v43
	v_mul_f32_e32 v132, v45, v45
	v_fmac_f32_e32 v131, v42, v42
	v_fmac_f32_e32 v132, v44, v44
	v_add_f32_e32 v131, v131, v132
	v_add_f32_e32 v130, v130, v131
	v_mul_f32_e32 v131, v39, v39
	v_mul_f32_e32 v132, v41, v41
	v_fmac_f32_e32 v131, v38, v38
	v_fmac_f32_e32 v132, v40, v40
	v_add_f32_e32 v131, v131, v132
	v_add_f32_e32 v130, v131, v130
	v_mul_f32_e32 v131, v35, v35
	v_mul_f32_e32 v132, v37, v37
	v_fmac_f32_e32 v131, v34, v34
	v_fmac_f32_e32 v132, v36, v36
	v_add_f32_e32 v131, v131, v132
	v_add_f32_e32 v130, v131, v130
	v_mov_b32_e32 v131, v130
	s_nop 1
	v_permlane16_swap_b32_e32 v130, v131
	s_waitcnt lgkmcnt(0)
	v_add_f32_e32 v130, v130, v131
	v_mov_b32_e32 v131, v130
	s_nop 1
	v_permlane32_swap_b32_e32 v130, v131
	s_and_saveexec_b64 s[12:13], s[6:7]
	s_cbranch_execz .LBB0_641
	s_lshl_b32 s0, s1, 10
	s_add_i32 s0, s15, s0
	v_lshl_add_u32 v132, v219, 4, s0
	s_waitcnt lgkmcnt(0)
	v_add_f32_e32 v130, v130, v131
	ds_write_b32 v132, v130 offset:2304
.LBB0_641:
	s_or_b64 exec, exec, s[12:13]
	v_mul_f32_e32 v130, v31, v31
	s_waitcnt lgkmcnt(0)
	v_mul_f32_e32 v131, v33, v33
	v_fmac_f32_e32 v130, v30, v30
	v_fmac_f32_e32 v131, v32, v32
	v_add_f32_e32 v130, v130, v131
	v_mul_f32_e32 v131, v27, v27
	v_mul_f32_e32 v132, v29, v29
	v_fmac_f32_e32 v131, v26, v26
	v_fmac_f32_e32 v132, v28, v28
	v_add_f32_e32 v131, v131, v132
	v_add_f32_e32 v130, v130, v131
	v_mul_f32_e32 v131, v23, v23
	v_mul_f32_e32 v132, v25, v25
	v_fmac_f32_e32 v131, v22, v22
	v_fmac_f32_e32 v132, v24, v24
	v_add_f32_e32 v131, v131, v132
	v_add_f32_e32 v130, v131, v130
	v_mul_f32_e32 v131, v19, v19
	v_mul_f32_e32 v132, v21, v21
	v_fmac_f32_e32 v131, v18, v18
	v_fmac_f32_e32 v132, v20, v20
	v_add_f32_e32 v131, v131, v132
	v_add_f32_e32 v130, v131, v130
	v_mov_b32_e32 v131, v130
	s_nop 1
	v_permlane16_swap_b32_e32 v130, v131
	s_waitcnt lgkmcnt(0)
	v_add_f32_e32 v130, v130, v131
	v_mov_b32_e32 v131, v130
	s_nop 1
	v_permlane32_swap_b32_e32 v130, v131
	s_and_saveexec_b64 s[12:13], s[6:7]
	s_cbranch_execz .LBB0_643
	s_lshl_b32 s0, s1, 10
	s_add_i32 s0, s15, s0
	v_lshl_add_u32 v132, v219, 4, s0
	s_waitcnt lgkmcnt(0)
	v_add_f32_e32 v130, v130, v131
	ds_write_b32 v132, v130 offset:2560
.LBB0_643:
	s_or_b64 exec, exec, s[12:13]
	v_mul_f32_e32 v130, v15, v15
	s_waitcnt lgkmcnt(0)
	v_mul_f32_e32 v131, v17, v17
	v_fmac_f32_e32 v130, v14, v14
	v_fmac_f32_e32 v131, v16, v16
	v_add_f32_e32 v130, v130, v131
	v_mul_f32_e32 v131, v11, v11
	v_mul_f32_e32 v132, v13, v13
	v_fmac_f32_e32 v131, v10, v10
	v_fmac_f32_e32 v132, v12, v12
	v_add_f32_e32 v131, v131, v132
	v_add_f32_e32 v130, v130, v131
	v_mul_f32_e32 v131, v7, v7
	v_mul_f32_e32 v132, v9, v9
	v_fmac_f32_e32 v131, v6, v6
	v_fmac_f32_e32 v132, v8, v8
	v_add_f32_e32 v131, v131, v132
	v_add_f32_e32 v130, v131, v130
	v_mul_f32_e32 v131, v3, v3
	v_mul_f32_e32 v132, v5, v5
	v_fmac_f32_e32 v131, v2, v2
	v_fmac_f32_e32 v132, v4, v4
	v_add_f32_e32 v131, v131, v132
	v_add_f32_e32 v130, v131, v130
	v_mov_b32_e32 v131, v130
	s_nop 1
	v_permlane16_swap_b32_e32 v130, v131
	s_waitcnt lgkmcnt(0)
	v_add_f32_e32 v130, v130, v131
	v_mov_b32_e32 v131, v130
	s_nop 1
	v_permlane32_swap_b32_e32 v130, v131
	s_and_saveexec_b64 s[12:13], s[6:7]
	s_cbranch_execz .LBB0_645
	s_lshl_b32 s0, s1, 10
	s_add_i32 s15, s15, s0
	v_lshl_add_u32 v132, v219, 4, s15
	s_waitcnt lgkmcnt(0)
	v_add_f32_e32 v130, v130, v131
	ds_write_b32 v132, v130 offset:2816

.LBB0_881:
	v_lshrrev_b32_e32 v214, 4, v1
	s_lshl_b32 s6, s10, 8
	s_lshl_b32 s2, s29, 8
	s_lshl_b32 s18, s31, 5
	v_lshl_or_b32 v130, v214, 3, s6
	s_add_i32 s4, s2, s30
	v_or_b32_e32 v178, s18, v130
	v_or_b32_e32 v130, s4, v213
	v_ashrrev_i32_e32 v179, 31, v178
	v_ashrrev_i32_e32 v131, 31, v130
	v_lshl_add_u64 v[132:133], v[178:179], 1, s[22:23]
	v_lshlrev_b64 v[134:135], 11, v[130:131]
	v_lshl_add_u64 v[134:135], v[132:133], 0, v[134:135]
	s_barrier
	v_lshlrev_b32_e32 v234, 4, v1
	v_add_u32_e32 v234, s36, v234
	v_add_u32_e32 v235, 0x10000, v234
	ds_read_b128 v[206:209], v235 offset:0
	ds_read_b128 v[202:205], v235 offset:8192
	v_or_b32_e32 v134, 16, v130
	v_ashrrev_i32_e32 v135, 31, v134
	v_lshlrev_b64 v[134:135], 11, v[134:135]
	v_lshl_add_u64 v[134:135], v[132:133], 0, v[134:135]
	ds_read_b128 v[198:201], v235 offset:16384
	ds_read_b128 v[186:189], v235 offset:24576
	v_or_b32_e32 v134, 32, v130
	v_ashrrev_i32_e32 v135, 31, v134
	v_lshlrev_b64 v[134:135], 11, v[134:135]
	v_lshl_add_u64 v[134:135], v[132:133], 0, v[134:135]
	ds_read_b128 v[174:177], v234 offset:0
	ds_read_b128 v[170:173], v234 offset:8192
	v_or_b32_e32 v134, 48, v130
	v_ashrrev_i32_e32 v135, 31, v134
	v_lshlrev_b64 v[134:135], 11, v[134:135]
	v_lshl_add_u64 v[134:135], v[132:133], 0, v[134:135]
	ds_read_b128 v[166:169], v234 offset:16384
	ds_read_b128 v[162:165], v234 offset:24576
	v_add_u32_e32 v134, 0x80, v130
	v_ashrrev_i32_e32 v135, 31, v134
	v_lshlrev_b64 v[134:135], 11, v[134:135]
	v_lshl_add_u64 v[134:135], v[132:133], 0, v[134:135]
	ds_read_b128 v[158:161], v235 offset:32768
	ds_read_b128 v[154:157], v235 offset:40960
	v_add_u32_e32 v134, 0x90, v130
	v_ashrrev_i32_e32 v135, 31, v134
	v_lshlrev_b64 v[134:135], 11, v[134:135]
	v_lshl_add_u64 v[134:135], v[132:133], 0, v[134:135]
	ds_read_b128 v[150:153], v235 offset:49152
	ds_read_b128 v[146:149], v235 offset:57344
	v_add_u32_e32 v134, 0xa0, v130
	v_add_u32_e32 v130, 0xb0, v130
	v_ashrrev_i32_e32 v135, 31, v134
	v_ashrrev_i32_e32 v131, 31, v130
	v_lshlrev_b64 v[134:135], 11, v[134:135]
	v_lshlrev_b64 v[130:131], 11, v[130:131]
	v_lshl_add_u64 v[134:135], v[132:133], 0, v[134:135]
	v_lshl_add_u64 v[130:131], v[132:133], 0, v[130:131]
	ds_read_b128 v[142:145], v234 offset:32768
	ds_read_b128 v[138:141], v234 offset:40960
	s_nop 0
	global_load_dwordx4 v[134:137], v[130:131], off
	s_nop 0
	global_load_dwordx4 v[130:133], v[130:131], off offset:256
	s_waitcnt lgkmcnt(0)
	s_barrier
	v_mul_f32_e32 v183, v127, v127
	v_mul_f32_e32 v184, v129, v129
	v_fmac_f32_e32 v183, v126, v126
	v_fmac_f32_e32 v184, v128, v128
	v_add_f32_e32 v183, v183, v184
	v_mul_f32_e32 v184, v123, v123
	v_mul_f32_e32 v185, v125, v125
	v_fmac_f32_e32 v184, v122, v122
	v_fmac_f32_e32 v185, v124, v124
	v_add_f32_e32 v184, v184, v185
	v_mbcnt_lo_u32_b32 v180, -1, 0
	v_add_f32_e32 v183, v184, v183
	v_mul_f32_e32 v184, v119, v119
	v_mul_f32_e32 v185, v121, v121
	v_mbcnt_hi_u32_b32 v181, -1, v180
	v_fmac_f32_e32 v184, v118, v118
	v_fmac_f32_e32 v185, v120, v120
	v_and_b32_e32 v182, 64, v181
	v_add_f32_e32 v184, v184, v185
	v_xor_b32_e32 v180, 16, v181
	v_add_u32_e32 v182, 64, v182
	v_add_f32_e32 v183, v184, v183
	v_mul_f32_e32 v184, v115, v115
	v_mul_f32_e32 v185, v117, v117
	v_cmp_lt_i32_e32 vcc, v180, v182
	v_fmac_f32_e32 v184, v114, v114
	v_fmac_f32_e32 v185, v116, v116
	v_cndmask_b32_e32 v180, v181, v180, vcc
	v_add_f32_e32 v184, v184, v185
	v_lshlrev_b32_e32 v180, 2, v180
	v_add_f32_e32 v183, v184, v183
	v_mov_b32_e32 v184, v183
	s_nop 1
	v_permlane16_swap_b32_e32 v183, v184
	v_xor_b32_e32 v185, 32, v181
	v_cmp_lt_i32_e32 vcc, v185, v182
	s_lshl_b32 s0, s31, 2
	s_add_i32 s3, s0, 0
	v_cndmask_b32_e32 v181, v181, v185, vcc
	v_lshlrev_b32_e32 v181, 2, v181
	s_waitcnt lgkmcnt(0)
	v_add_f32_e32 v182, v183, v184
	v_mov_b32_e32 v183, v182
	s_nop 1
	v_permlane32_swap_b32_e32 v182, v183
	v_cmp_gt_u32_e32 vcc, 16, v1
	s_and_saveexec_b64 s[0:1], vcc
	s_cbranch_execz .LBB0_883
	s_lshl_b32 s5, s11, 10
	s_add_i32 s5, s3, s5
	v_lshl_add_u32 v184, v213, 4, s5
	s_waitcnt lgkmcnt(0)
	v_add_f32_e32 v182, v182, v183
	ds_write_b32 v184, v182
.LBB0_883:
	s_or_b64 exec, exec, s[0:1]
	v_mul_f32_e32 v182, v111, v111
	s_waitcnt lgkmcnt(0)
	v_mul_f32_e32 v183, v113, v113
	v_fmac_f32_e32 v182, v110, v110
	v_fmac_f32_e32 v183, v112, v112
	v_add_f32_e32 v182, v182, v183
	v_mul_f32_e32 v183, v107, v107
	v_mul_f32_e32 v184, v109, v109
	v_fmac_f32_e32 v183, v106, v106
	v_fmac_f32_e32 v184, v108, v108
	v_add_f32_e32 v183, v183, v184
	v_add_f32_e32 v182, v183, v182
	v_mul_f32_e32 v183, v103, v103
	v_mul_f32_e32 v184, v105, v105
	v_fmac_f32_e32 v183, v102, v102
	v_fmac_f32_e32 v184, v104, v104
	v_add_f32_e32 v183, v183, v184
	v_add_f32_e32 v182, v183, v182
	v_mul_f32_e32 v183, v99, v99
	v_mul_f32_e32 v184, v101, v101
	v_fmac_f32_e32 v183, v98, v98
	v_fmac_f32_e32 v184, v100, v100
	v_add_f32_e32 v183, v183, v184
	v_add_f32_e32 v182, v183, v182
	v_mov_b32_e32 v183, v182
	s_nop 1
	v_permlane16_swap_b32_e32 v182, v183
	s_waitcnt lgkmcnt(0)
	v_add_f32_e32 v182, v182, v183
	v_mov_b32_e32 v183, v182
	s_nop 1
	v_permlane32_swap_b32_e32 v182, v183
	s_and_saveexec_b64 s[0:1], vcc
	s_cbranch_execz .LBB0_885
	s_lshl_b32 s5, s11, 10
	s_add_i32 s5, s3, s5
	v_lshl_add_u32 v184, v213, 4, s5
	s_waitcnt lgkmcnt(0)
	v_add_f32_e32 v182, v182, v183
	ds_write_b32 v184, v182 offset:256
.LBB0_885:
	s_or_b64 exec, exec, s[0:1]
	v_mul_f32_e32 v182, v95, v95
	s_waitcnt lgkmcnt(0)
	v_mul_f32_e32 v183, v97, v97
	v_fmac_f32_e32 v182, v94, v94
	v_fmac_f32_e32 v183, v96, v96
	v_add_f32_e32 v182, v182, v183
	v_mul_f32_e32 v183, v91, v91
	v_mul_f32_e32 v184, v93, v93
	v_fmac_f32_e32 v183, v90, v90
	v_fmac_f32_e32 v184, v92, v92
	v_add_f32_e32 v183, v183, v184
	v_add_f32_e32 v182, v183, v182
	v_mul_f32_e32 v183, v87, v87
	v_mul_f32_e32 v184, v89, v89
	v_fmac_f32_e32 v183, v86, v86
	v_fmac_f32_e32 v184, v88, v88
	v_add_f32_e32 v183, v183, v184
	v_add_f32_e32 v182, v183, v182
	v_mul_f32_e32 v183, v83, v83
	v_mul_f32_e32 v184, v85, v85
	v_fmac_f32_e32 v183, v82, v82
	v_fmac_f32_e32 v184, v84, v84
	v_add_f32_e32 v183, v183, v184
	v_add_f32_e32 v182, v183, v182
	v_mov_b32_e32 v183, v182
	s_nop 1
	v_permlane16_swap_b32_e32 v182, v183
	s_waitcnt lgkmcnt(0)
	v_add_f32_e32 v182, v182, v183
	v_mov_b32_e32 v183, v182
	s_nop 1
	v_permlane32_swap_b32_e32 v182, v183
	s_and_saveexec_b64 s[0:1], vcc
	s_cbranch_execz .LBB0_887
	s_lshl_b32 s5, s11, 10
	s_add_i32 s5, s3, s5
	v_lshl_add_u32 v184, v213, 4, s5
	s_waitcnt lgkmcnt(0)
	v_add_f32_e32 v182, v182, v183
	ds_write_b32 v184, v182 offset:512
.LBB0_887:
	s_or_b64 exec, exec, s[0:1]
	v_mul_f32_e32 v182, v79, v79
	s_waitcnt lgkmcnt(0)
	v_mul_f32_e32 v183, v81, v81
	v_fmac_f32_e32 v182, v78, v78
	v_fmac_f32_e32 v183, v80, v80
	v_add_f32_e32 v182, v182, v183
	v_mul_f32_e32 v183, v75, v75
	v_mul_f32_e32 v184, v77, v77
	v_fmac_f32_e32 v183, v74, v74
	v_fmac_f32_e32 v184, v76, v76
	v_add_f32_e32 v183, v183, v184
	v_add_f32_e32 v182, v183, v182
	v_mul_f32_e32 v183, v71, v71
	v_mul_f32_e32 v184, v73, v73
	v_fmac_f32_e32 v183, v70, v70
	v_fmac_f32_e32 v184, v72, v72
	v_add_f32_e32 v183, v183, v184
	v_add_f32_e32 v182, v183, v182
	v_mul_f32_e32 v183, v67, v67
	v_mul_f32_e32 v184, v69, v69
	v_fmac_f32_e32 v183, v66, v66
	v_fmac_f32_e32 v184, v68, v68
	v_add_f32_e32 v183, v183, v184
	v_add_f32_e32 v182, v183, v182
	v_mov_b32_e32 v183, v182
	s_nop 1
	v_permlane16_swap_b32_e32 v182, v183
	s_waitcnt lgkmcnt(0)
	v_add_f32_e32 v182, v182, v183
	v_mov_b32_e32 v183, v182
	s_nop 1
	v_permlane32_swap_b32_e32 v182, v183
	s_and_saveexec_b64 s[0:1], vcc
	s_cbranch_execz .LBB0_889
	s_lshl_b32 s5, s11, 10
	s_add_i32 s5, s3, s5
	v_lshl_add_u32 v184, v213, 4, s5
	s_waitcnt lgkmcnt(0)
	v_add_f32_e32 v182, v182, v183
	ds_write_b32 v184, v182 offset:768
.LBB0_889:
	s_or_b64 exec, exec, s[0:1]
	v_mul_f32_e32 v182, v63, v63
	s_waitcnt lgkmcnt(0)
	v_mul_f32_e32 v183, v65, v65
	v_fmac_f32_e32 v182, v62, v62
	v_fmac_f32_e32 v183, v64, v64
	v_add_f32_e32 v182, v182, v183
	v_mul_f32_e32 v183, v59, v59
	v_mul_f32_e32 v184, v61, v61
	v_fmac_f32_e32 v183, v58, v58
	v_fmac_f32_e32 v184, v60, v60
	v_add_f32_e32 v183, v183, v184
	v_add_f32_e32 v182, v183, v182
	v_mul_f32_e32 v183, v55, v55
	v_mul_f32_e32 v184, v57, v57
	v_fmac_f32_e32 v183, v54, v54
	v_fmac_f32_e32 v184, v56, v56
	v_add_f32_e32 v183, v183, v184
	v_add_f32_e32 v182, v183, v182
	v_mul_f32_e32 v183, v51, v51
	v_mul_f32_e32 v184, v53, v53
	v_fmac_f32_e32 v183, v50, v50
	v_fmac_f32_e32 v184, v52, v52
	v_add_f32_e32 v183, v183, v184
	v_add_f32_e32 v182, v183, v182
	v_mov_b32_e32 v183, v182
	s_nop 1
	v_permlane16_swap_b32_e32 v182, v183
	s_waitcnt lgkmcnt(0)
	v_add_f32_e32 v182, v182, v183
	v_mov_b32_e32 v183, v182
	s_nop 1
	v_permlane32_swap_b32_e32 v182, v183
	s_and_saveexec_b64 s[0:1], vcc
	s_cbranch_execz .LBB0_891
	s_lshl_b32 s5, s11, 10
	s_add_i32 s5, s3, s5
	v_lshl_add_u32 v184, v213, 4, s5
	s_waitcnt lgkmcnt(0)
	v_add_f32_e32 v182, v182, v183
	ds_write_b32 v184, v182 offset:2048
.LBB0_891:
	s_or_b64 exec, exec, s[0:1]
	v_mul_f32_e32 v182, v47, v47
	s_waitcnt lgkmcnt(0)
	v_mul_f32_e32 v183, v49, v49
	v_fmac_f32_e32 v182, v46, v46
	v_fmac_f32_e32 v183, v48, v48
	v_add_f32_e32 v182, v182, v183
	v_mul_f32_e32 v183, v43, v43
	v_mul_f32_e32 v184, v45, v45
	v_fmac_f32_e32 v183, v42, v42
	v_fmac_f32_e32 v184, v44, v44
	v_add_f32_e32 v183, v183, v184
	v_add_f32_e32 v182, v183, v182
	v_mul_f32_e32 v183, v39, v39
	v_mul_f32_e32 v184, v41, v41
	v_fmac_f32_e32 v183, v38, v38
	v_fmac_f32_e32 v184, v40, v40
	v_add_f32_e32 v183, v183, v184
	v_add_f32_e32 v182, v183, v182
	v_mul_f32_e32 v183, v35, v35
	v_mul_f32_e32 v184, v37, v37
	v_fmac_f32_e32 v183, v34, v34
	v_fmac_f32_e32 v184, v36, v36
	v_add_f32_e32 v183, v183, v184
	v_add_f32_e32 v182, v183, v182
	v_mov_b32_e32 v183, v182
	s_nop 1
	v_permlane16_swap_b32_e32 v182, v183
	s_waitcnt lgkmcnt(0)
	v_add_f32_e32 v182, v182, v183
	v_mov_b32_e32 v183, v182
	s_nop 1
	v_permlane32_swap_b32_e32 v182, v183
	s_and_saveexec_b64 s[0:1], vcc
	s_cbranch_execz .LBB0_893
	s_lshl_b32 s5, s11, 10
	s_add_i32 s5, s3, s5
	v_lshl_add_u32 v184, v213, 4, s5
	s_waitcnt lgkmcnt(0)
	v_add_f32_e32 v182, v182, v183
	ds_write_b32 v184, v182 offset:2304
.LBB0_893:
	s_or_b64 exec, exec, s[0:1]
	v_mul_f32_e32 v182, v31, v31
	s_waitcnt lgkmcnt(0)
	v_mul_f32_e32 v183, v33, v33
	v_fmac_f32_e32 v182, v30, v30
	v_fmac_f32_e32 v183, v32, v32
	v_add_f32_e32 v182, v182, v183
	v_mul_f32_e32 v183, v27, v27
	v_mul_f32_e32 v184, v29, v29
	v_fmac_f32_e32 v183, v26, v26
	v_fmac_f32_e32 v184, v28, v28
	v_add_f32_e32 v183, v183, v184
	v_add_f32_e32 v182, v183, v182
	v_mul_f32_e32 v183, v23, v23
	v_mul_f32_e32 v184, v25, v25
	v_fmac_f32_e32 v183, v22, v22
	v_fmac_f32_e32 v184, v24, v24
	v_add_f32_e32 v183, v183, v184
	v_add_f32_e32 v182, v183, v182
	v_mul_f32_e32 v183, v19, v19
	v_mul_f32_e32 v184, v21, v21
	v_fmac_f32_e32 v183, v18, v18
	v_fmac_f32_e32 v184, v20, v20
	v_add_f32_e32 v183, v183, v184
	v_add_f32_e32 v182, v183, v182
	v_mov_b32_e32 v183, v182
	s_nop 1
	v_permlane16_swap_b32_e32 v182, v183
	s_waitcnt lgkmcnt(0)
	v_add_f32_e32 v182, v182, v183
	v_mov_b32_e32 v183, v182
	s_nop 1
	v_permlane32_swap_b32_e32 v182, v183
	s_and_saveexec_b64 s[0:1], vcc
	s_cbranch_execz .LBB0_895
	s_lshl_b32 s5, s11, 10
	s_add_i32 s5, s3, s5
	v_lshl_add_u32 v184, v213, 4, s5
	s_waitcnt lgkmcnt(0)
	v_add_f32_e32 v182, v182, v183
	ds_write_b32 v184, v182 offset:2560
.LBB0_895:
	s_or_b64 exec, exec, s[0:1]
	v_mul_f32_e32 v182, v15, v15
	s_waitcnt lgkmcnt(0)
	v_mul_f32_e32 v183, v17, v17
	v_fmac_f32_e32 v182, v14, v14
	v_fmac_f32_e32 v183, v16, v16
	v_add_f32_e32 v182, v182, v183
	v_mul_f32_e32 v183, v11, v11
	v_mul_f32_e32 v184, v13, v13
	v_fmac_f32_e32 v183, v10, v10
	v_fmac_f32_e32 v184, v12, v12
	v_add_f32_e32 v183, v183, v184
	v_add_f32_e32 v182, v183, v182
	v_mul_f32_e32 v183, v7, v7
	v_mul_f32_e32 v184, v9, v9
	v_fmac_f32_e32 v183, v6, v6
	v_fmac_f32_e32 v184, v8, v8
	v_add_f32_e32 v183, v183, v184
	v_add_f32_e32 v182, v183, v182
	v_mul_f32_e32 v183, v3, v3
	v_mul_f32_e32 v184, v5, v5
	v_fmac_f32_e32 v183, v2, v2
	v_fmac_f32_e32 v184, v4, v4
	v_add_f32_e32 v183, v183, v184
	v_add_f32_e32 v182, v183, v182
	v_mov_b32_e32 v180, v182
	s_nop 1
	v_permlane16_swap_b32_e32 v182, v180
	s_waitcnt lgkmcnt(0)
	v_add_f32_e32 v180, v182, v180
	v_mov_b32_e32 v181, v180
	s_nop 1
	v_permlane32_swap_b32_e32 v180, v181
	s_and_saveexec_b64 s[0:1], vcc
	s_cbranch_execz .LBB0_897
	s_lshl_b32 s5, s11, 10
	s_add_i32 s3, s3, s5
	v_lshl_add_u32 v182, v213, 4, s3
	s_waitcnt lgkmcnt(0)
	v_add_f32_e32 v180, v180, v181
	ds_write_b32 v182, v180 offset:2816
